# ffn_out sample-row tiles (128x32): 3-stage LDS-DMA ring with two k-steps in flight
# speedup vs baseline: 1.0063x; 1.0063x over previous
.LBB0_2425:
	v_and_b32_e32 v2, 15, v0
	v_ashrrev_i32_e32 v3, 1, v0
	v_lshrrev_b32_e32 v0, 2, v0
	v_and_b32_e32 v27, 28, v0
	v_cvt_f32_ubyte0_e32 v0, s9
	v_rcp_iflag_f32_e32 v0, v0
	s_lshl_b64 s[0:1], s[0:1], 1
	s_waitcnt lgkmcnt(0)
	s_add_u32 s15, s6, s0
	s_addc_u32 s16, s7, s1
	v_mul_f32_e32 v0, 0x4f7ffffe, v0
	v_cvt_u32_f32_e32 v0, v0
	s_cmp_lt_i32 s8, 0
	s_movk_i32 s17, 0xffc0
	s_cselect_b64 s[0:1], -1, 0
	v_and_or_b32 v26, v3, s17, v2
	s_sub_i32 s17, 0, s9
	v_readfirstlane_b32 s18, v0
	s_mul_i32 s17, s17, s18
	s_mul_hi_u32 s17, s18, s17
	s_add_i32 s17, s18, s17
	s_add_u32 s11, s6, s11
	s_addc_u32 s10, s7, s10
	v_readlane_b32 s21, v249, 1
	s_nop 0
	s_cmpk_lg_u32 s21, 0x200
	s_cbranch_scc1 .LBB0_2427
	s_load_dwordx2 s[36:37], s[84:85], 0x130
	v_readlane_b32 s21, v249, 0
	s_nop 0
	s_and_b32 s22, s21, 7
	s_lshr_b32 s23, s21, 3
	s_add_i32 s22, s22, 0x80
	s_mul_i32 s21, s22, 0xb0000
	s_add_u32 s24, s4, s21
	s_addc_u32 s25, s5, 0
	s_mul_i32 s21, s23, 0x2c000
	s_add_u32 s28, s11, s21
	s_addc_u32 s29, s10, 0
	s_waitcnt lgkmcnt(0)
	s_lshl_b32 s21, s22, 19
	s_lshl_b32 s23, s23, 7
	s_add_i32 s21, s21, s23
	s_add_u32 s34, s36, s21
	s_addc_u32 s35, s37, 0
	v_and_b32_e32 v77, 7, v196
	v_bfe_u32 v78, v196, 4, 2
	v_bfe_u32 v79, v196, 6, 1
	v_lshl_or_b32 v80, v79, 2, v78
	v_xor_b32_e32 v77, v77, v80
	v_lshrrev_b32_e32 v80, 3, v196
	v_mul_u32_u24_e32 v80, 0x1600, v80
	v_lshl_or_b32 v68, v77, 4, v80
	v_add_u32_e32 v69, 0x2c000, v68
	v_add_u32_e32 v70, 0x58000, v68
	v_add_u32_e32 v71, 0x84000, v68
	v_and_b32_e32 v77, 15, v196
	v_bfe_u32 v80, v196, 1, 3
	v_xor_b32_e32 v80, v78, v80
	v_lshlrev_b32_e32 v80, 4, v80
	v_xor_b32_e32 v81, 64, v80
	v_lshlrev_b32_e32 v77, 7, v77
	v_lshrrev_b32_e32 v82, 7, v196
	v_lshl_or_b32 v82, v82, 13, v77
	v_lshl_or_b32 v83, v79, 11, v77
	v_add_u32_e32 v73, v82, v80
	v_add_u32_e32 v74, v82, v81
	v_add_u32_e32 v75, v83, v80
	v_add_u32_e32 v76, v83, v81
	v_readfirstlane_b32 s27, v196
	s_lshr_b32 s27, s27, 6
	s_lshl_b32 s27, s27, 10
	s_barrier
	s_add_i32 m0, s27, 0x0
	s_nop 0
	global_load_lds_dwordx4 v68, s[24:25]
	s_add_i32 m0, s27, 0x1000
	s_nop 0
	global_load_lds_dwordx4 v69, s[24:25]
	s_add_i32 m0, s27, 0x2000
	s_nop 0
	global_load_lds_dwordx4 v70, s[24:25]
	s_add_i32 m0, s27, 0x3000
	s_nop 0
	global_load_lds_dwordx4 v71, s[24:25]
	s_add_i32 m0, s27, 0x4000
	s_nop 0
	global_load_lds_dwordx4 v68, s[28:29]
	s_add_u32 s24, s24, 0x80
	s_addc_u32 s25, s25, 0
	s_add_u32 s28, s28, 0x80
	s_addc_u32 s29, s29, 0
	s_add_i32 m0, s27, 0x5000
	s_nop 0
	global_load_lds_dwordx4 v68, s[24:25]
	s_add_i32 m0, s27, 0x6000
	s_nop 0
	global_load_lds_dwordx4 v69, s[24:25]
	s_add_i32 m0, s27, 0x7000
	s_nop 0
	global_load_lds_dwordx4 v70, s[24:25]
	s_add_i32 m0, s27, 0x8000
	s_nop 0
	global_load_lds_dwordx4 v71, s[24:25]
	s_add_i32 m0, s27, 0x9000
	s_nop 0
	global_load_lds_dwordx4 v68, s[28:29]
	s_add_u32 s24, s24, 0x80
	s_addc_u32 s25, s25, 0
	s_add_u32 s28, s28, 0x80
	s_addc_u32 s29, s29, 0
	v_mov_b64_e32 v[2:3], 0
	v_mov_b64_e32 v[4:5], 0
	v_mov_b64_e32 v[6:7], 0
	v_mov_b64_e32 v[8:9], 0
	v_mov_b64_e32 v[10:11], 0
	v_mov_b64_e32 v[12:13], 0
	v_mov_b64_e32 v[14:15], 0
	v_mov_b64_e32 v[16:17], 0
	s_movk_i32 s30, 14
.Lr1o_k:
	s_waitcnt vmcnt(5)
	s_barrier
	s_add_i32 m0, s27, 0xa000
	s_nop 0
	global_load_lds_dwordx4 v68, s[24:25]
	s_add_i32 m0, s27, 0xb000
	s_nop 0
	global_load_lds_dwordx4 v69, s[24:25]
	s_add_i32 m0, s27, 0xc000
	s_nop 0
	global_load_lds_dwordx4 v70, s[24:25]
	s_add_i32 m0, s27, 0xd000
	s_nop 0
	global_load_lds_dwordx4 v71, s[24:25]
	s_add_i32 m0, s27, 0xe000
	s_nop 0
	global_load_lds_dwordx4 v68, s[28:29]
	s_add_u32 s24, s24, 0x80
	s_addc_u32 s25, s25, 0
	s_add_u32 s28, s28, 0x80
	s_addc_u32 s29, s29, 0
	ds_read_b128 v[28:31], v73 offset:0
	ds_read_b128 v[32:35], v73 offset:2048
	ds_read_b128 v[36:39], v73 offset:4096
	ds_read_b128 v[40:43], v73 offset:6144
	ds_read_b128 v[44:47], v75 offset:16384
	ds_read_b128 v[48:51], v74 offset:0
	ds_read_b128 v[52:55], v74 offset:2048
	ds_read_b128 v[56:59], v74 offset:4096
	ds_read_b128 v[60:63], v74 offset:6144
	ds_read_b128 v[64:67], v76 offset:16384
	s_waitcnt lgkmcnt(5)
	v_mfma_f32_16x16x32_bf16 v[2:5], v[44:47], v[28:31], v[2:5]
	v_mfma_f32_16x16x32_bf16 v[6:9], v[44:47], v[32:35], v[6:9]
	v_mfma_f32_16x16x32_bf16 v[10:13], v[44:47], v[36:39], v[10:13]
	v_mfma_f32_16x16x32_bf16 v[14:17], v[44:47], v[40:43], v[14:17]
	s_waitcnt lgkmcnt(0)
	v_mfma_f32_16x16x32_bf16 v[2:5], v[64:67], v[48:51], v[2:5]
	v_mfma_f32_16x16x32_bf16 v[6:9], v[64:67], v[52:55], v[6:9]
	v_mfma_f32_16x16x32_bf16 v[10:13], v[64:67], v[56:59], v[10:13]
	v_mfma_f32_16x16x32_bf16 v[14:17], v[64:67], v[60:63], v[14:17]
	s_waitcnt vmcnt(5)
	s_barrier
	s_add_i32 m0, s27, 0x0
	s_nop 0
	global_load_lds_dwordx4 v68, s[24:25]
	s_add_i32 m0, s27, 0x1000
	s_nop 0
	global_load_lds_dwordx4 v69, s[24:25]
	s_add_i32 m0, s27, 0x2000
	s_nop 0
	global_load_lds_dwordx4 v70, s[24:25]
	s_add_i32 m0, s27, 0x3000
	s_nop 0
	global_load_lds_dwordx4 v71, s[24:25]
	s_add_i32 m0, s27, 0x4000
	s_nop 0
	global_load_lds_dwordx4 v68, s[28:29]
	s_add_u32 s24, s24, 0x80
	s_addc_u32 s25, s25, 0
	s_add_u32 s28, s28, 0x80
	s_addc_u32 s29, s29, 0
	ds_read_b128 v[28:31], v73 offset:20480
	ds_read_b128 v[32:35], v73 offset:22528
	ds_read_b128 v[36:39], v73 offset:24576
	ds_read_b128 v[40:43], v73 offset:26624
	ds_read_b128 v[44:47], v75 offset:36864
	ds_read_b128 v[48:51], v74 offset:20480
	ds_read_b128 v[52:55], v74 offset:22528
	ds_read_b128 v[56:59], v74 offset:24576
	ds_read_b128 v[60:63], v74 offset:26624
	ds_read_b128 v[64:67], v76 offset:36864
	s_waitcnt lgkmcnt(5)
	v_mfma_f32_16x16x32_bf16 v[2:5], v[44:47], v[28:31], v[2:5]
	v_mfma_f32_16x16x32_bf16 v[6:9], v[44:47], v[32:35], v[6:9]
	v_mfma_f32_16x16x32_bf16 v[10:13], v[44:47], v[36:39], v[10:13]
	v_mfma_f32_16x16x32_bf16 v[14:17], v[44:47], v[40:43], v[14:17]
	s_waitcnt lgkmcnt(0)
	v_mfma_f32_16x16x32_bf16 v[2:5], v[64:67], v[48:51], v[2:5]
	v_mfma_f32_16x16x32_bf16 v[6:9], v[64:67], v[52:55], v[6:9]
	v_mfma_f32_16x16x32_bf16 v[10:13], v[64:67], v[56:59], v[10:13]
	v_mfma_f32_16x16x32_bf16 v[14:17], v[64:67], v[60:63], v[14:17]
	s_waitcnt vmcnt(5)
	s_barrier
	s_add_i32 m0, s27, 0x5000
	s_nop 0
	global_load_lds_dwordx4 v68, s[24:25]
	s_add_i32 m0, s27, 0x6000
	s_nop 0
	global_load_lds_dwordx4 v69, s[24:25]
	s_add_i32 m0, s27, 0x7000
	s_nop 0
	global_load_lds_dwordx4 v70, s[24:25]
	s_add_i32 m0, s27, 0x8000
	s_nop 0
	global_load_lds_dwordx4 v71, s[24:25]
	s_add_i32 m0, s27, 0x9000
	s_nop 0
	global_load_lds_dwordx4 v68, s[28:29]
	s_add_u32 s24, s24, 0x80
	s_addc_u32 s25, s25, 0
	s_add_u32 s28, s28, 0x80
	s_addc_u32 s29, s29, 0
	ds_read_b128 v[28:31], v73 offset:40960
	ds_read_b128 v[32:35], v73 offset:43008
	ds_read_b128 v[36:39], v73 offset:45056
	ds_read_b128 v[40:43], v73 offset:47104
	ds_read_b128 v[44:47], v75 offset:57344
	ds_read_b128 v[48:51], v74 offset:40960
	ds_read_b128 v[52:55], v74 offset:43008
	ds_read_b128 v[56:59], v74 offset:45056
	ds_read_b128 v[60:63], v74 offset:47104
	ds_read_b128 v[64:67], v76 offset:57344
	s_waitcnt lgkmcnt(5)
	v_mfma_f32_16x16x32_bf16 v[2:5], v[44:47], v[28:31], v[2:5]
	v_mfma_f32_16x16x32_bf16 v[6:9], v[44:47], v[32:35], v[6:9]
	v_mfma_f32_16x16x32_bf16 v[10:13], v[44:47], v[36:39], v[10:13]
	v_mfma_f32_16x16x32_bf16 v[14:17], v[44:47], v[40:43], v[14:17]
	s_waitcnt lgkmcnt(0)
	v_mfma_f32_16x16x32_bf16 v[2:5], v[64:67], v[48:51], v[2:5]
	v_mfma_f32_16x16x32_bf16 v[6:9], v[64:67], v[52:55], v[6:9]
	v_mfma_f32_16x16x32_bf16 v[10:13], v[64:67], v[56:59], v[10:13]
	v_mfma_f32_16x16x32_bf16 v[14:17], v[64:67], v[60:63], v[14:17]
	s_add_i32 s30, s30, -1
	s_cmp_lg_u32 s30, 0
	s_cbranch_scc1 .Lr1o_k
	s_waitcnt vmcnt(5)
	s_barrier
	ds_read_b128 v[28:31], v73 offset:0
	ds_read_b128 v[32:35], v73 offset:2048
	ds_read_b128 v[36:39], v73 offset:4096
	ds_read_b128 v[40:43], v73 offset:6144
	ds_read_b128 v[44:47], v75 offset:16384
	ds_read_b128 v[48:51], v74 offset:0
	ds_read_b128 v[52:55], v74 offset:2048
	ds_read_b128 v[56:59], v74 offset:4096
	ds_read_b128 v[60:63], v74 offset:6144
	ds_read_b128 v[64:67], v76 offset:16384
	s_waitcnt lgkmcnt(5)
	v_mfma_f32_16x16x32_bf16 v[2:5], v[44:47], v[28:31], v[2:5]
	v_mfma_f32_16x16x32_bf16 v[6:9], v[44:47], v[32:35], v[6:9]
	v_mfma_f32_16x16x32_bf16 v[10:13], v[44:47], v[36:39], v[10:13]
	v_mfma_f32_16x16x32_bf16 v[14:17], v[44:47], v[40:43], v[14:17]
	s_waitcnt lgkmcnt(0)
	v_mfma_f32_16x16x32_bf16 v[2:5], v[64:67], v[48:51], v[2:5]
	v_mfma_f32_16x16x32_bf16 v[6:9], v[64:67], v[52:55], v[6:9]
	v_mfma_f32_16x16x32_bf16 v[10:13], v[64:67], v[56:59], v[10:13]
	v_mfma_f32_16x16x32_bf16 v[14:17], v[64:67], v[60:63], v[14:17]
	s_waitcnt vmcnt(0)
	s_barrier
	ds_read_b128 v[28:31], v73 offset:20480
	ds_read_b128 v[32:35], v73 offset:22528
	ds_read_b128 v[36:39], v73 offset:24576
	ds_read_b128 v[40:43], v73 offset:26624
	ds_read_b128 v[44:47], v75 offset:36864
	ds_read_b128 v[48:51], v74 offset:20480
	ds_read_b128 v[52:55], v74 offset:22528
	ds_read_b128 v[56:59], v74 offset:24576
	ds_read_b128 v[60:63], v74 offset:26624
	ds_read_b128 v[64:67], v76 offset:36864
	s_waitcnt lgkmcnt(5)
	v_mfma_f32_16x16x32_bf16 v[2:5], v[44:47], v[28:31], v[2:5]
	v_mfma_f32_16x16x32_bf16 v[6:9], v[44:47], v[32:35], v[6:9]
	v_mfma_f32_16x16x32_bf16 v[10:13], v[44:47], v[36:39], v[10:13]
	v_mfma_f32_16x16x32_bf16 v[14:17], v[44:47], v[40:43], v[14:17]
	s_waitcnt lgkmcnt(0)
	v_mfma_f32_16x16x32_bf16 v[2:5], v[64:67], v[48:51], v[2:5]
	v_mfma_f32_16x16x32_bf16 v[6:9], v[64:67], v[52:55], v[6:9]
	v_mfma_f32_16x16x32_bf16 v[10:13], v[64:67], v[56:59], v[10:13]
	v_mfma_f32_16x16x32_bf16 v[14:17], v[64:67], v[60:63], v[14:17]
	v_lshrrev_b32_e32 v77, 7, v196
	v_and_b32_e32 v78, 15, v196
	v_lshl_or_b32 v77, v77, 6, v78
	v_lshlrev_b32_e32 v77, 12, v77
	v_bfe_u32 v78, v196, 6, 1
	v_bfe_u32 v79, v196, 4, 2
	v_lshlrev_b32_e32 v78, 6, v78
	v_lshl_or_b32 v78, v79, 4, v78
	v_add_u32_e32 v84, v77, v78
	v_add_u32_e32 v85, 0x10000, v84
	v_add_u32_e32 v86, 0x20000, v84
	v_add_u32_e32 v87, 0x30000, v84
	global_load_dwordx4 v[88:91], v84, s[34:35]
	global_load_dwordx4 v[92:95], v85, s[34:35]
	global_load_dwordx4 v[96:99], v86, s[34:35]
	global_load_dwordx4 v[100:103], v87, s[34:35]
	s_waitcnt vmcnt(0)
	v_pk_add_f32 v[2:3], v[2:3], v[88:89]
	v_pk_add_f32 v[4:5], v[4:5], v[90:91]
	v_pk_add_f32 v[6:7], v[6:7], v[92:93]
	v_pk_add_f32 v[8:9], v[8:9], v[94:95]
	v_pk_add_f32 v[10:11], v[10:11], v[96:97]
	v_pk_add_f32 v[12:13], v[12:13], v[98:99]
	v_pk_add_f32 v[14:15], v[14:15], v[100:101]
	v_pk_add_f32 v[16:17], v[16:17], v[102:103]
	global_store_dwordx4 v84, v[2:5], s[34:35]
	global_store_dwordx4 v85, v[6:9], s[34:35]
	global_store_dwordx4 v86, v[10:13], s[34:35]
	global_store_dwordx4 v87, v[14:17], s[34:35]
	s_branch .LBB0_2435
